# combined: wide attention epilogue stores via LDS, transposed scan stage 2 with 8-byte stores, epilogue shuffles via permlane swap
# speedup vs baseline: 1.0037x; 1.0037x over previous
.LBB0_1625:
	v_add_f32_dpp v64, v157, v157 quad_perm:[1,0,3,2] row_mask:0xf bank_mask:0xf bound_ctrl:1
	v_add_f32_dpp v65, v156, v156 quad_perm:[1,0,3,2] row_mask:0xf bank_mask:0xf bound_ctrl:1
	v_add_f32_dpp v66, v155, v155 quad_perm:[1,0,3,2] row_mask:0xf bank_mask:0xf bound_ctrl:1
	v_add_f32_dpp v67, v154, v154 quad_perm:[1,0,3,2] row_mask:0xf bank_mask:0xf bound_ctrl:1
	v_add_f32_dpp v64, v64, v64 quad_perm:[2,3,0,1] row_mask:0xf bank_mask:0xf bound_ctrl:1
	v_add_f32_dpp v65, v65, v65 quad_perm:[2,3,0,1] row_mask:0xf bank_mask:0xf bound_ctrl:1
	v_add_f32_dpp v66, v66, v66 quad_perm:[2,3,0,1] row_mask:0xf bank_mask:0xf bound_ctrl:1
	v_add_f32_dpp v67, v67, v67 quad_perm:[2,3,0,1] row_mask:0xf bank_mask:0xf bound_ctrl:1
	v_add_f32_dpp v64, v64, v64 row_half_mirror row_mask:0xf bank_mask:0xf bound_ctrl:1
	v_add_f32_dpp v65, v65, v65 row_half_mirror row_mask:0xf bank_mask:0xf bound_ctrl:1
	v_add_f32_dpp v66, v66, v66 row_half_mirror row_mask:0xf bank_mask:0xf bound_ctrl:1
	v_add_f32_dpp v67, v67, v67 row_half_mirror row_mask:0xf bank_mask:0xf bound_ctrl:1
	v_add_f32_dpp v64, v64, v64 row_mirror row_mask:0xf bank_mask:0xf bound_ctrl:1
	v_add_f32_dpp v65, v65, v65 row_mirror row_mask:0xf bank_mask:0xf bound_ctrl:1
	v_add_f32_dpp v66, v66, v66 row_mirror row_mask:0xf bank_mask:0xf bound_ctrl:1
	v_add_f32_dpp v67, v67, v67 row_mirror row_mask:0xf bank_mask:0xf bound_ctrl:1
	s_waitcnt vmcnt(0)
	v_div_scale_f32 v68, s[6:7], v64, v64, 1.0
	v_rcp_f32_e32 v69, v68
	v_div_scale_f32 v70, vcc, 1.0, v64, 1.0
	v_fma_f32 v71, -v68, v69, 1.0
	v_fmac_f32_e32 v69, v71, v69
	v_mul_f32_e32 v71, v70, v69
	v_fma_f32 v72, -v68, v71, v70
	v_fmac_f32_e32 v71, v72, v69
	v_fma_f32 v68, -v68, v71, v70
	v_div_fmas_f32 v68, v68, v69, v71
	v_div_fixup_f32 v64, v68, v64, 1.0
	v_div_scale_f32 v68, s[6:7], v65, v65, 1.0
	v_rcp_f32_e32 v69, v68
	v_div_scale_f32 v70, vcc, 1.0, v65, 1.0
	v_fma_f32 v71, -v68, v69, 1.0
	v_fmac_f32_e32 v69, v71, v69
	v_mul_f32_e32 v71, v70, v69
	v_fma_f32 v72, -v68, v71, v70
	v_fmac_f32_e32 v71, v72, v69
	v_fma_f32 v68, -v68, v71, v70
	v_div_fmas_f32 v68, v68, v69, v71
	v_div_fixup_f32 v65, v68, v65, 1.0
	v_div_scale_f32 v68, s[6:7], v66, v66, 1.0
	v_rcp_f32_e32 v69, v68
	v_div_scale_f32 v70, vcc, 1.0, v66, 1.0
	v_fma_f32 v71, -v68, v69, 1.0
	v_fmac_f32_e32 v69, v71, v69
	v_mul_f32_e32 v71, v70, v69
	v_fma_f32 v72, -v68, v71, v70
	v_fmac_f32_e32 v71, v72, v69
	v_fma_f32 v68, -v68, v71, v70
	v_div_fmas_f32 v68, v68, v69, v71
	v_div_fixup_f32 v66, v68, v66, 1.0
	v_div_scale_f32 v68, s[6:7], v67, v67, 1.0
	v_rcp_f32_e32 v69, v68
	v_div_scale_f32 v70, vcc, 1.0, v67, 1.0
	v_fma_f32 v71, -v68, v69, 1.0
	v_fmac_f32_e32 v69, v71, v69
	v_mul_f32_e32 v71, v70, v69
	v_fma_f32 v72, -v68, v71, v70
	v_fmac_f32_e32 v71, v72, v69
	v_fma_f32 v68, -v68, v71, v70
	v_div_fmas_f32 v68, v68, v69, v71
	v_div_fixup_f32 v67, v68, v67, 1.0
	s_movk_i32 s6, 0x330
	v_mad_u32_u24 v2, v188, s6, v218
	v_mul_u32_u24_e32 v3, 14, v187
	v_sub_u32_e32 v2, v2, v3
	v_lshlrev_b32_e32 v3, 8, v188
	v_lshl_or_b32 v3, v187, 4, v3
	v_readfirstlane_b32 s96, v176
	v_readfirstlane_b32 s97, v177
	s_nop 1
	s_add_u32 s96, s96, s10
	s_addc_u32 s97, s97, s11
	v_pk_mul_f32 v[60:61], v[60:61], v[64:65]
	v_pk_mul_f32 v[62:63], v[62:63], v[66:67]
	v_pk_mul_f32 v[56:57], v[56:57], v[64:65]
	v_pk_mul_f32 v[58:59], v[58:59], v[66:67]
	v_pk_mul_f32 v[52:53], v[52:53], v[64:65]
	v_pk_mul_f32 v[54:55], v[54:55], v[66:67]
	v_pk_mul_f32 v[48:49], v[48:49], v[64:65]
	v_pk_mul_f32 v[50:51], v[50:51], v[66:67]
	v_pk_mul_f32 v[44:45], v[44:45], v[64:65]
	v_pk_mul_f32 v[46:47], v[46:47], v[66:67]
	v_pk_mul_f32 v[40:41], v[40:41], v[64:65]
	v_pk_mul_f32 v[42:43], v[42:43], v[66:67]
	v_pk_mul_f32 v[36:37], v[36:37], v[64:65]
	v_pk_mul_f32 v[38:39], v[38:39], v[66:67]
	v_pk_mul_f32 v[32:33], v[32:33], v[64:65]
	v_pk_mul_f32 v[34:35], v[34:35], v[66:67]
	v_cvt_pk_bf16_f32 v4, v60, v61
	v_cvt_pk_bf16_f32 v5, v62, v63
	v_cvt_pk_bf16_f32 v6, v56, v57
	v_cvt_pk_bf16_f32 v7, v58, v59
	v_cvt_pk_bf16_f32 v8, v52, v53
	v_cvt_pk_bf16_f32 v9, v54, v55
	v_cvt_pk_bf16_f32 v10, v48, v49
	v_cvt_pk_bf16_f32 v11, v50, v51
	v_cvt_pk_bf16_f32 v12, v44, v45
	v_cvt_pk_bf16_f32 v13, v46, v47
	v_cvt_pk_bf16_f32 v14, v40, v41
	v_cvt_pk_bf16_f32 v15, v42, v43
	v_cvt_pk_bf16_f32 v16, v36, v37
	v_cvt_pk_bf16_f32 v17, v38, v39
	v_cvt_pk_bf16_f32 v18, v32, v33
	v_cvt_pk_bf16_f32 v19, v34, v35
	ds_write_b16 v2, v4 offset:0
	ds_write_b16_d16_hi v2, v4 offset:272
	ds_write_b16 v2, v5 offset:544
	ds_write_b16_d16_hi v2, v5 offset:816
	ds_write_b16 v2, v6 offset:32
	ds_write_b16_d16_hi v2, v6 offset:304
	ds_write_b16 v2, v7 offset:576
	ds_write_b16_d16_hi v2, v7 offset:848
	ds_write_b16 v2, v8 offset:64
	ds_write_b16_d16_hi v2, v8 offset:336
	ds_write_b16 v2, v9 offset:608
	ds_write_b16_d16_hi v2, v9 offset:880
	ds_write_b16 v2, v10 offset:96
	ds_write_b16_d16_hi v2, v10 offset:368
	ds_write_b16 v2, v11 offset:640
	ds_write_b16_d16_hi v2, v11 offset:912
	ds_write_b16 v2, v12 offset:128
	ds_write_b16_d16_hi v2, v12 offset:400
	ds_write_b16 v2, v13 offset:672
	ds_write_b16_d16_hi v2, v13 offset:944
	ds_write_b16 v2, v14 offset:160
	ds_write_b16_d16_hi v2, v14 offset:432
	ds_write_b16 v2, v15 offset:704
	ds_write_b16_d16_hi v2, v15 offset:976
	ds_write_b16 v2, v16 offset:192
	ds_write_b16_d16_hi v2, v16 offset:464
	ds_write_b16 v2, v17 offset:736
	ds_write_b16_d16_hi v2, v17 offset:1008
	ds_write_b16 v2, v18 offset:224
	ds_write_b16_d16_hi v2, v18 offset:496
	ds_write_b16 v2, v19 offset:768
	ds_write_b16_d16_hi v2, v19 offset:1040
	s_waitcnt lgkmcnt(0)
	ds_read_b128 v[76:79], v218
	ds_read_b128 v[80:83], v218 offset:1088
	ds_read_b128 v[84:87], v218 offset:2176
	ds_read_b128 v[88:91], v218 offset:3264
	s_waitcnt lgkmcnt(3)
	global_store_dwordx4 v3, v[76:79], s[96:97]
	s_waitcnt lgkmcnt(2)
	global_store_dwordx4 v3, v[80:83], s[96:97] offset:1024
	s_waitcnt lgkmcnt(1)
	global_store_dwordx4 v3, v[84:87], s[96:97] offset:2048
	s_waitcnt lgkmcnt(0)
	global_store_dwordx4 v3, v[88:91], s[96:97] offset:3072
	s_waitcnt lgkmcnt(0)
	s_branch .Lunit_bar
